# gated-DeltaNet scan: MFMA sections re-emitted with LDS fragment reads pipelined in a ring of free registers (same MFMAs, same accumulator registers)
# speedup vs baseline: 1.4112x; 1.0103x over previous
.LBB0_523:
	v_lshl_add_u64 v[96:97], s[30:31], 0, v[144:145]
	s_movk_i32 s0, 0x1000
	v_add_co_u32_e32 v172, vcc, s0, v96
	s_movk_i32 s0, 0x5000
	s_nop 0
	v_addc_co_u32_e32 v173, vcc, 0, v97, vcc
	v_add_co_u32_e32 v170, vcc, s48, v96
	s_add_u32 s12, s30, s2
	s_nop 0
	v_addc_co_u32_e32 v171, vcc, 0, v97, vcc
	v_add_co_u32_e32 v168, vcc, s56, v96
	s_addc_u32 s13, s31, s3
	s_nop 0
	v_addc_co_u32_e32 v169, vcc, 0, v97, vcc
	v_add_co_u32_e32 v166, vcc, s0, v96
	global_load_dword v112, v192, s[12:13] sc1
	s_nop 0
	v_addc_co_u32_e32 v167, vcc, 0, v97, vcc
	global_load_ushort v234, v[172:173], off offset:256
	global_load_ushort v233, v[172:173], off offset:288
	global_load_ushort v232, v[172:173], off offset:320
	global_load_ushort v231, v[172:173], off offset:352
	global_load_ushort v230, v[170:171], off offset:2560
	global_load_ushort v229, v[170:171], off offset:2592
	global_load_ushort v228, v[170:171], off offset:2624
	global_load_ushort v227, v[170:171], off offset:2656
	global_load_ushort v226, v[168:169], off offset:768
	global_load_ushort v225, v[168:169], off offset:800
	global_load_ushort v224, v[168:169], off offset:832
	global_load_ushort v223, v[168:169], off offset:864
	global_load_ushort v181, v[166:167], off offset:3072
	global_load_ushort v180, v[166:167], off offset:3104
	global_load_ushort v179, v[166:167], off offset:3136
	global_load_ushort v178, v[166:167], off offset:3168
	s_mov_b32 s0, 0x358637bd
	s_waitcnt vmcnt(15)
	v_cvt_f32_f16_e32 v235, v234
	v_mul_f32_e64 v82, v82, v112
	v_mul_f32_e64 v83, v83, v112
	v_pk_mul_f32 v[80:81], v[80:81], v[112:113] op_sel_hi:[1,0]
	v_pk_mul_f32 v[86:87], v[86:87], v[112:113] op_sel_hi:[1,0]
	v_mul_f32_e64 v84, v84, v112
	v_mul_f32_e64 v85, v85, v112
	v_pk_mul_f32 v[90:91], v[90:91], v[112:113] op_sel_hi:[1,0]
	v_pk_mul_f32 v[88:89], v[88:89], v[112:113] op_sel_hi:[1,0]
	v_pk_mul_f32 v[94:95], v[94:95], v[112:113] op_sel_hi:[1,0]
	v_pk_mul_f32 v[92:93], v[92:93], v[112:113] op_sel_hi:[1,0]
	ds_read_b128 v[108:111], v116 offset:46080
	ds_read_b128 v[240:243], v117
	ds_read_b128 v[244:247], v117 offset:2304
	ds_read_b128 v[252:255], v117 offset:4608
	s_waitcnt lgkmcnt(2)
	v_mfma_f32_16x16x32_f16 v[236:239], v[108:111], v[240:243], 0
	ds_read_b128 v[240:243], v117 offset:6912
	ds_read_b128 v[174:177], v116 offset:46144
	s_waitcnt lgkmcnt(3)
	v_mfma_f32_16x16x32_f16 v[104:107], v[108:111], v[244:247], 0
	ds_read_b128 v[244:247], v117 offset:64
	s_waitcnt lgkmcnt(3)
	v_mfma_f32_16x16x32_f16 v[100:103], v[108:111], v[252:255], 0
	ds_read_b128 v[252:255], v117 offset:2368
	s_waitcnt lgkmcnt(3)
	v_mfma_f32_16x16x32_f16 v[96:99], v[108:111], v[240:243], 0
	ds_read_b128 v[240:243], v117 offset:4672
	s_waitcnt lgkmcnt(2)
	v_mfma_f32_16x16x32_f16 v[236:239], v[174:177], v[244:247], v[236:239]
	ds_read_b128 v[244:247], v117 offset:6976
	s_waitcnt lgkmcnt(2)
	v_mfma_f32_16x16x32_f16 v[104:107], v[174:177], v[252:255], v[104:107]
	s_waitcnt lgkmcnt(1)
	v_mfma_f32_16x16x32_f16 v[100:103], v[174:177], v[240:243], v[100:103]
	s_waitcnt lgkmcnt(0)
	v_mfma_f32_16x16x32_f16 v[96:99], v[174:177], v[244:247], v[96:99]
	ds_read_b64 v[108:109], v214 offset:9216
	s_waitcnt lgkmcnt(0)
	v_cvt_f32_f16_e32 v110, v108
	v_cvt_f32_f16_sdwa v108, v108 dst_sel:DWORD dst_unused:UNUSED_PAD src0_sel:WORD_1
	v_sub_f32_e32 v110, v110, v236
	v_sub_f32_e32 v108, v108, v237
	v_med3_f32 v108, v108, s57, v194
	v_cvt_f16_f32_e32 v108, v108
	v_med3_f32 v110, v110, s57, v194
	v_cvt_f16_f32_e32 v110, v110
	ds_write_b16 v215, v108 offset:55440
	v_cvt_f32_f16_e32 v108, v109
	ds_write_b16 v215, v110 offset:55296
	v_sub_f32_e32 v108, v108, v238
	v_med3_f32 v108, v108, s57, v194
	v_cvt_f16_f32_e32 v108, v108
	ds_write_b16 v215, v108 offset:55584
	v_cvt_f32_f16_sdwa v108, v109 dst_sel:DWORD dst_unused:UNUSED_PAD src0_sel:WORD_1
	v_sub_f32_e32 v108, v108, v239
	v_med3_f32 v108, v108, s57, v194
	v_cvt_f16_f32_e32 v108, v108
	ds_write_b16 v215, v108 offset:55728
	ds_read_b64 v[108:109], v214 offset:11520
	s_waitcnt lgkmcnt(0)
	v_cvt_f32_f16_e32 v110, v108
	v_sub_f32_e32 v104, v110, v104
	v_med3_f32 v104, v104, s57, v194
	v_cvt_f16_f32_e32 v104, v104
	ds_write_b16 v215, v104 offset:55328
	v_cvt_f32_f16_sdwa v104, v108 dst_sel:DWORD dst_unused:UNUSED_PAD src0_sel:WORD_1
	v_sub_f32_e32 v104, v104, v105
	v_med3_f32 v104, v104, s57, v194
	v_cvt_f16_f32_e32 v104, v104
	ds_write_b16 v216, v104 offset:55440
	v_cvt_f32_f16_e32 v104, v109
	v_sub_f32_e32 v104, v104, v106
	v_med3_f32 v104, v104, s57, v194
	v_cvt_f16_f32_e32 v104, v104
	ds_write_b16 v216, v104 offset:55584
	v_cvt_f32_f16_sdwa v104, v109 dst_sel:DWORD dst_unused:UNUSED_PAD src0_sel:WORD_1
	v_sub_f32_e32 v104, v104, v107
	v_med3_f32 v104, v104, s57, v194
	v_cvt_f16_f32_e32 v104, v104
	ds_write_b16 v216, v104 offset:55728
	ds_read_b64 v[104:105], v214 offset:13824
	s_waitcnt lgkmcnt(0)
	v_cvt_f32_f16_e32 v106, v104
	v_sub_f32_e32 v100, v106, v100
	v_med3_f32 v100, v100, s57, v194
	v_cvt_f16_f32_e32 v100, v100
	ds_write_b16 v215, v100 offset:55360
	v_cvt_f32_f16_sdwa v100, v104 dst_sel:DWORD dst_unused:UNUSED_PAD src0_sel:WORD_1
	v_sub_f32_e32 v100, v100, v101
	v_med3_f32 v100, v100, s57, v194
	v_cvt_f16_f32_e32 v100, v100
	ds_write_b16 v217, v100 offset:55440
	v_cvt_f32_f16_e32 v100, v105
	v_sub_f32_e32 v100, v100, v102
	v_med3_f32 v100, v100, s57, v194
	v_cvt_f16_f32_e32 v100, v100
	ds_write_b16 v217, v100 offset:55584
	v_cvt_f32_f16_sdwa v100, v105 dst_sel:DWORD dst_unused:UNUSED_PAD src0_sel:WORD_1
	v_sub_f32_e32 v100, v100, v103
	v_med3_f32 v100, v100, s57, v194
	v_cvt_f16_f32_e32 v100, v100
	ds_write_b16 v217, v100 offset:55728
	ds_read_b64 v[100:101], v214 offset:16128
	s_waitcnt lgkmcnt(0)
	v_cvt_f32_f16_e32 v102, v100
	v_sub_f32_e32 v96, v102, v96
	v_med3_f32 v96, v96, s57, v194
	v_cvt_f16_f32_e32 v96, v96
	ds_write_b16 v215, v96 offset:55392
	v_cvt_f32_f16_sdwa v96, v100 dst_sel:DWORD dst_unused:UNUSED_PAD src0_sel:WORD_1
	v_sub_f32_e32 v96, v96, v97
	v_med3_f32 v96, v96, s57, v194
	v_cvt_f16_f32_e32 v96, v96
	ds_write_b16 v218, v96 offset:55440
	v_cvt_f32_f16_e32 v96, v101
	v_sub_f32_e32 v96, v96, v98
	v_med3_f32 v96, v96, s57, v194
	v_cvt_f16_f32_e32 v96, v96
	ds_write_b16 v218, v96 offset:55584
	v_cvt_f32_f16_sdwa v96, v101 dst_sel:DWORD dst_unused:UNUSED_PAD src0_sel:WORD_1
	v_sub_f32_e32 v96, v96, v99
	v_med3_f32 v96, v96, s57, v194
	v_cvt_f16_f32_e32 v96, v96
	ds_write_b16 v218, v96 offset:55728
	s_waitcnt lgkmcnt(0)
	s_barrier
	ds_write_b128 v115, v[0:3]
	ds_write_b128 v209, v[4:7]
	ds_write_b128 v219, v[8:11]
	ds_write_b128 v210, v[12:15]
	global_load_dword v234, v[118:119], off
	ds_read_b128 v[174:177], v116 offset:27648
	ds_read_b128 v[240:243], v117 offset:46080
	ds_read_b128 v[244:247], v117 offset:48384
	ds_read_b128 v[252:255], v117 offset:50688
	s_waitcnt lgkmcnt(2)
	v_mfma_f32_16x16x32_f16 v[108:111], v[174:177], v[240:243], 0
	ds_read_b128 v[240:243], v117 offset:52992
	ds_read_b128 v[236:239], v116 offset:27712
	s_waitcnt lgkmcnt(3)
	v_mfma_f32_16x16x32_f16 v[104:107], v[174:177], v[244:247], 0
	ds_read_b128 v[244:247], v117 offset:46144
	s_waitcnt lgkmcnt(3)
	v_mfma_f32_16x16x32_f16 v[100:103], v[174:177], v[252:255], 0
	ds_read_b128 v[252:255], v117 offset:48448
	s_waitcnt lgkmcnt(3)
	v_mfma_f32_16x16x32_f16 v[96:99], v[174:177], v[240:243], 0
	ds_read_b128 v[240:243], v117 offset:50752
	s_waitcnt lgkmcnt(2)
	v_mfma_f32_16x16x32_f16 v[108:111], v[236:239], v[244:247], v[108:111]
	ds_read_b128 v[244:247], v117 offset:53056
	ds_read_b128 v[174:177], v116 offset:18432
	s_waitcnt lgkmcnt(3)
	v_mfma_f32_16x16x32_f16 v[104:107], v[236:239], v[252:255], v[104:107]
	ds_read_b128 v[252:255], v117 offset:55296
	s_waitcnt lgkmcnt(3)
	v_mfma_f32_16x16x32_f16 v[100:103], v[236:239], v[240:243], v[100:103]
	ds_read_b128 v[240:243], v117 offset:57600
	s_waitcnt lgkmcnt(3)
	v_mfma_f32_16x16x32_f16 v[96:99], v[236:239], v[244:247], v[96:99]
	ds_read_b128 v[244:247], v117 offset:59904
	s_waitcnt lgkmcnt(2)
	v_mfma_f32_16x16x32_f16 v[108:111], v[174:177], v[252:255], v[108:111]
	ds_read_b128 v[252:255], v117 offset:62208
	ds_read_b128 v[236:239], v116 offset:18496
	s_waitcnt lgkmcnt(3)
	v_mfma_f32_16x16x32_f16 v[104:107], v[174:177], v[240:243], v[104:107]
	ds_read_b128 v[240:243], v117 offset:55360
	s_waitcnt lgkmcnt(3)
	v_mfma_f32_16x16x32_f16 v[100:103], v[174:177], v[244:247], v[100:103]
	ds_read_b128 v[244:247], v117 offset:57664
	s_waitcnt lgkmcnt(3)
	v_mfma_f32_16x16x32_f16 v[96:99], v[174:177], v[252:255], v[96:99]
	ds_read_b128 v[252:255], v117 offset:59968
	s_waitcnt lgkmcnt(2)
	v_mfma_f32_16x16x32_f16 v[108:111], v[236:239], v[240:243], v[108:111]
	ds_read_b128 v[240:243], v117 offset:62272
	s_waitcnt lgkmcnt(2)
	v_mfma_f32_16x16x32_f16 v[104:107], v[236:239], v[244:247], v[104:107]
	s_waitcnt lgkmcnt(1)
	v_mfma_f32_16x16x32_f16 v[100:103], v[236:239], v[252:255], v[100:103]
	s_waitcnt lgkmcnt(0)
	v_mfma_f32_16x16x32_f16 v[96:99], v[236:239], v[240:243], v[96:99]
	v_mul_f32_e32 v236, 0xbfb8aa3b, v235
	v_exp_f32_e32 v236, v236
	v_mov_b32_e32 v174, v108
	v_mov_b32_e32 v175, v104
	v_pk_mul_f32 v[176:177], v[174:175], v[174:175]
	v_add_f32_e32 v236, 1.0, v236
	v_div_scale_f32 v237, s[8:9], v236, v236, v235
	v_rcp_f32_e32 v238, v237
	v_mov_b32_e32 v174, v100
	v_mov_b32_e32 v175, v96
	v_pk_mul_f32 v[174:175], v[174:175], v[174:175]
	v_fma_f32 v239, -v237, v238, 1.0
	v_fmac_f32_e32 v238, v239, v238
	v_div_scale_f32 v239, vcc, v235, v236, v235
	v_mul_f32_e32 v240, v239, v238
	v_fma_f32 v241, -v237, v240, v239
	v_fmac_f32_e32 v240, v241, v238
	v_fma_f32 v237, -v237, v240, v239
	v_div_fmas_f32 v237, v237, v238, v240
	v_div_fixup_f32 v235, v237, v236, v235
	s_waitcnt vmcnt(15)
	v_cvt_f32_f16_e32 v236, v233
	global_load_dword v233, v[118:119], off offset:64
	v_mul_f32_e32 v237, 0xbfb8aa3b, v236
	v_exp_f32_e32 v237, v237
	s_nop 0
	v_add_f32_e32 v237, 1.0, v237
	v_div_scale_f32 v238, s[8:9], v237, v237, v236
	v_rcp_f32_e32 v239, v238
	s_nop 0
	v_fma_f32 v240, -v238, v239, 1.0
	v_fmac_f32_e32 v239, v240, v239
	v_div_scale_f32 v240, vcc, v236, v237, v236
	v_mul_f32_e32 v241, v240, v239
	v_fma_f32 v242, -v238, v241, v240
	v_fmac_f32_e32 v241, v242, v239
	v_fma_f32 v238, -v238, v241, v240
	v_div_fmas_f32 v238, v238, v239, v241
	v_div_fixup_f32 v242, v238, v237, v236
	s_waitcnt vmcnt(15)
	v_cvt_f32_f16_e32 v236, v232
	global_load_dword v232, v[118:119], off offset:128
	v_mul_f32_e32 v237, 0xbfb8aa3b, v236
	v_exp_f32_e32 v237, v237
	s_nop 0
	v_add_f32_e32 v237, 1.0, v237
	v_div_scale_f32 v238, s[8:9], v237, v237, v236
	v_rcp_f32_e32 v239, v238
	s_nop 0
	v_fma_f32 v240, -v238, v239, 1.0
	v_fmac_f32_e32 v239, v240, v239
	v_div_scale_f32 v240, vcc, v236, v237, v236
	v_mul_f32_e32 v241, v240, v239
	v_fma_f32 v243, -v238, v241, v240
	v_fmac_f32_e32 v241, v243, v239
	v_fma_f32 v238, -v238, v241, v240
	v_div_fmas_f32 v238, v238, v239, v241
	v_div_fixup_f32 v243, v238, v237, v236
	s_waitcnt vmcnt(15)
	v_cvt_f32_f16_e32 v236, v231
	global_load_dword v231, v[118:119], off offset:192
	v_mul_f32_e32 v237, 0xbfb8aa3b, v236
	v_exp_f32_e32 v237, v237
	s_nop 0
	v_add_f32_e32 v237, 1.0, v237
	v_div_scale_f32 v238, s[8:9], v237, v237, v236
	v_rcp_f32_e32 v239, v238
	s_nop 0
	v_fma_f32 v240, -v238, v239, 1.0
	v_fmac_f32_e32 v239, v240, v239
	v_div_scale_f32 v240, vcc, v236, v237, v236
	v_mul_f32_e32 v241, v240, v239
	v_fma_f32 v244, -v238, v241, v240
	v_fmac_f32_e32 v241, v244, v239
	v_fma_f32 v238, -v238, v241, v240
	v_div_fmas_f32 v238, v238, v239, v241
	v_div_fixup_f32 v244, v238, v237, v236
	v_mov_b32_e32 v236, v109
	v_mov_b32_e32 v237, v105
	v_pk_mul_f32 v[236:237], v[236:237], v[236:237]
	v_mov_b32_e32 v238, v101
	v_mov_b32_e32 v239, v97
	v_pk_mul_f32 v[238:239], v[238:239], v[238:239]
	v_mov_b32_e32 v240, v236
	v_mov_b32_e32 v241, v176
	v_mov_b32_e32 v176, v237
	v_pk_add_f32 v[176:177], v[240:241], v[176:177]
	v_mov_b32_e32 v236, v238
	v_mov_b32_e32 v237, v174
	v_pk_add_f32 v[176:177], v[176:177], v[236:237]
	v_mov_b32_e32 v174, v239
	v_pk_add_f32 v[174:175], v[176:177], v[174:175]
	s_nop 1
	v_mov_b32_dpp v177, v175 quad_perm:[1,0,3,2] row_mask:0xf bank_mask:0xf bound_ctrl:1
	v_mov_b32_dpp v176, v174 quad_perm:[1,0,3,2] row_mask:0xf bank_mask:0xf bound_ctrl:1
	v_pk_add_f32 v[174:175], v[174:175], v[176:177]
	s_nop 1
	v_mov_b32_dpp v177, v175 quad_perm:[2,3,0,1] row_mask:0xf bank_mask:0xf bound_ctrl:1
	v_mov_b32_dpp v176, v174 quad_perm:[2,3,0,1] row_mask:0xf bank_mask:0xf bound_ctrl:1
	v_pk_add_f32 v[174:175], v[174:175], v[176:177]
	s_nop 1
	v_mov_b32_dpp v177, v175 row_ror:4 row_mask:0xf bank_mask:0xf bound_ctrl:1
	v_mov_b32_dpp v176, v174 row_ror:4 row_mask:0xf bank_mask:0xf bound_ctrl:1
	v_pk_add_f32 v[174:175], v[174:175], v[176:177]
	s_nop 1
	v_mov_b32_dpp v177, v175 row_ror:8 row_mask:0xf bank_mask:0xf bound_ctrl:1
	v_mov_b32_dpp v176, v174 row_ror:8 row_mask:0xf bank_mask:0xf bound_ctrl:1
	v_pk_add_f32 v[176:177], v[174:175], v[176:177]
	v_mov_b64_e32 v[174:175], s[0:1]
	s_mov_b32 s0, 0x3c800000
	v_pk_fma_f32 v[176:177], v[176:177], s[0:1], v[174:175] op_sel_hi:[1,0,0]
	s_nop 0
	v_mul_f32_e32 v236, 0x4b800000, v177
	v_cmp_gt_f32_e64 s[8:9], s49, v177
	v_cmp_gt_f32_e32 vcc, s49, v176
	s_nop 0
	v_cndmask_b32_e64 v177, v177, v236, s[8:9]
	v_rsq_f32_e32 v177, v177
	s_nop 0
	v_mul_f32_e32 v236, 0x45800000, v177
	v_cndmask_b32_e64 v177, v177, v236, s[8:9]
	v_mul_f32_e32 v96, v96, v177
	v_mul_f32_e32 v100, v100, v177
	s_waitcnt vmcnt(1)
	v_mul_f32_e32 v100, v232, v100
	v_mul_f32_e32 v100, v243, v100
	v_med3_f32 v100, v100, s57, v194
	s_waitcnt vmcnt(0)
	v_mul_f32_e32 v96, v231, v96
	v_mul_f32_e32 v96, v244, v96
	v_med3_f32 v96, v96, s57, v194
	v_cvt_f16_f32_e32 v96, v96
	v_cvt_f16_f32_e32 v100, v100
	v_mul_f32_e32 v108, v108, v177
	v_mul_f32_e32 v108, v234, v108
	global_store_short v[172:173], v96, off offset:352
	v_mul_f32_e32 v96, 0x4b800000, v176
	v_cndmask_b32_e32 v96, v176, v96, vcc
	v_rsq_f32_e32 v96, v96
	v_mul_f32_e32 v108, v235, v108
	v_med3_f32 v108, v108, s57, v194
	global_store_short v[172:173], v100, off offset:320
	v_mul_f32_e32 v100, 0x45800000, v96
	v_cvt_f16_f32_e32 v108, v108
	v_cndmask_b32_e32 v96, v96, v100, vcc
	v_cvt_f32_f16_e32 v100, v230
	v_mul_f32_e32 v104, v104, v177
	v_mul_f32_e32 v104, v233, v104
	global_store_short v[172:173], v108, off offset:256
	v_mul_f32_e32 v104, v242, v104
	v_mul_f32_e32 v108, 0xbfb8aa3b, v100
	v_med3_f32 v104, v104, s57, v194
	v_exp_f32_e32 v108, v108
	v_cvt_f16_f32_e32 v104, v104
	v_mul_f32_e32 v101, v101, v96
	v_mul_f32_e32 v101, v232, v101
	v_add_f32_e32 v108, 1.0, v108
	global_store_short v[172:173], v104, off offset:288
	v_mul_f32_e32 v104, v109, v96
	v_div_scale_f32 v109, s[8:9], v108, v108, v100
	v_rcp_f32_e32 v172, v109
	v_mul_f32_e32 v104, v234, v104
	v_fma_f32 v173, -v109, v172, 1.0
	v_fmac_f32_e32 v172, v173, v172
	v_div_scale_f32 v173, vcc, v100, v108, v100
	v_mul_f32_e32 v176, v173, v172
	v_fma_f32 v177, -v109, v176, v173
	v_fmac_f32_e32 v176, v177, v172
	v_fma_f32 v109, -v109, v176, v173
	v_div_fmas_f32 v109, v109, v172, v176
	v_div_fixup_f32 v100, v109, v108, v100
	v_mul_f32_e32 v100, v100, v104
	v_med3_f32 v100, v100, s57, v194
	v_cvt_f16_f32_e32 v100, v100
	v_mul_f32_e32 v104, v105, v96
	v_mul_f32_e32 v104, v233, v104
	v_mul_f32_e32 v96, v97, v96
	global_store_short v[170:171], v100, off offset:2560
	v_cvt_f32_f16_e32 v100, v229
	v_mul_f32_e32 v96, v231, v96
	v_mul_f32_e32 v105, 0xbfb8aa3b, v100
	v_exp_f32_e32 v105, v105
	s_nop 0
	v_add_f32_e32 v105, 1.0, v105
	v_div_scale_f32 v108, s[8:9], v105, v105, v100
	v_rcp_f32_e32 v109, v108
	s_nop 0
	v_fma_f32 v172, -v108, v109, 1.0
	v_fmac_f32_e32 v109, v172, v109
	v_div_scale_f32 v172, vcc, v100, v105, v100
	v_mul_f32_e32 v173, v172, v109
	v_fma_f32 v176, -v108, v173, v172
	v_fmac_f32_e32 v173, v176, v109
	v_fma_f32 v108, -v108, v173, v172
	v_div_fmas_f32 v108, v108, v109, v173
	v_div_fixup_f32 v100, v108, v105, v100
	v_mul_f32_e32 v100, v100, v104
	v_med3_f32 v100, v100, s57, v194
	v_cvt_f16_f32_e32 v100, v100
	global_store_short v[170:171], v100, off offset:2592
	v_cvt_f32_f16_e32 v100, v228
	v_mul_f32_e32 v104, 0xbfb8aa3b, v100
	v_exp_f32_e32 v104, v104
	s_nop 0
	v_add_f32_e32 v104, 1.0, v104
	v_div_scale_f32 v105, s[8:9], v104, v104, v100
	v_rcp_f32_e32 v108, v105
	s_nop 0
	v_fma_f32 v109, -v105, v108, 1.0
	v_fmac_f32_e32 v108, v109, v108
	v_div_scale_f32 v109, vcc, v100, v104, v100
	v_mul_f32_e32 v172, v109, v108
	v_fma_f32 v173, -v105, v172, v109
	v_fmac_f32_e32 v172, v173, v108
	v_fma_f32 v105, -v105, v172, v109
	v_div_fmas_f32 v105, v105, v108, v172
	v_div_fixup_f32 v100, v105, v104, v100
	v_mul_f32_e32 v100, v100, v101
	v_med3_f32 v100, v100, s57, v194
	v_cvt_f16_f32_e32 v100, v100
	global_store_short v[170:171], v100, off offset:2624
	v_cvt_f32_f16_e32 v100, v227
	v_mul_f32_e32 v97, 0xbfb8aa3b, v100
	v_exp_f32_e32 v97, v97
	s_nop 0
	v_add_f32_e32 v97, 1.0, v97
	v_div_scale_f32 v101, s[8:9], v97, v97, v100
	v_rcp_f32_e32 v104, v101
	s_nop 0
	v_fma_f32 v105, -v101, v104, 1.0
	v_fmac_f32_e32 v104, v105, v104
	v_div_scale_f32 v105, vcc, v100, v97, v100
	v_mul_f32_e32 v108, v105, v104
	v_fma_f32 v109, -v101, v108, v105
	v_fmac_f32_e32 v108, v109, v104
	v_fma_f32 v101, -v101, v108, v105
	v_div_fmas_f32 v101, v101, v104, v108
	v_cvt_f32_f16_e32 v104, v226
	v_div_fixup_f32 v97, v101, v97, v100
	v_mul_f32_e32 v96, v97, v96
	v_med3_f32 v96, v96, s57, v194
	v_mul_f32_e32 v105, 0xbfb8aa3b, v104
	v_exp_f32_e32 v105, v105
	v_cvt_f16_f32_e32 v96, v96
	v_mov_b32_e32 v97, v106
	v_add_f32_e32 v105, 1.0, v105
	v_div_scale_f32 v108, s[8:9], v105, v105, v104
	v_rcp_f32_e32 v109, v108
	global_store_short v[170:171], v96, off offset:2656
	v_mov_b32_e32 v96, v110
	v_pk_mul_f32 v[100:101], v[96:97], v[96:97]
	v_fma_f32 v170, -v108, v109, 1.0
	v_fmac_f32_e32 v109, v170, v109
	v_div_scale_f32 v170, vcc, v104, v105, v104
	v_mul_f32_e32 v171, v170, v109
	v_fma_f32 v172, -v108, v171, v170
	v_fmac_f32_e32 v171, v172, v109
	v_fma_f32 v108, -v108, v171, v170
	v_div_fmas_f32 v108, v108, v109, v171
	v_div_fixup_f32 v172, v108, v105, v104
	v_cvt_f32_f16_e32 v104, v225
	v_mov_b32_e32 v96, v102
	v_mov_b32_e32 v97, v98
	v_pk_mul_f32 v[96:97], v[96:97], v[96:97]
	v_mul_f32_e32 v105, 0xbfb8aa3b, v104
	v_exp_f32_e32 v105, v105
	s_nop 0
	v_add_f32_e32 v105, 1.0, v105
	v_div_scale_f32 v108, s[8:9], v105, v105, v104
	v_rcp_f32_e32 v109, v108
	s_nop 0
	v_fma_f32 v170, -v108, v109, 1.0
	v_fmac_f32_e32 v109, v170, v109
	v_div_scale_f32 v170, vcc, v104, v105, v104
	v_mul_f32_e32 v171, v170, v109
	v_fma_f32 v173, -v108, v171, v170
	v_fmac_f32_e32 v171, v173, v109
	v_fma_f32 v108, -v108, v171, v170
	v_div_fmas_f32 v108, v108, v109, v171
	v_div_fixup_f32 v173, v108, v105, v104
	v_cvt_f32_f16_e32 v104, v224
	v_mul_f32_e32 v105, 0xbfb8aa3b, v104
	v_exp_f32_e32 v105, v105
	s_nop 0
	v_add_f32_e32 v105, 1.0, v105
	v_div_scale_f32 v108, s[8:9], v105, v105, v104
	v_rcp_f32_e32 v109, v108
	s_nop 0
	v_fma_f32 v170, -v108, v109, 1.0
	v_fmac_f32_e32 v109, v170, v109
	v_div_scale_f32 v170, vcc, v104, v105, v104
	v_mul_f32_e32 v171, v170, v109
	v_fma_f32 v176, -v108, v171, v170
	v_fmac_f32_e32 v171, v176, v109
	v_fma_f32 v108, -v108, v171, v170
	v_div_fmas_f32 v108, v108, v109, v171
	v_div_fixup_f32 v176, v108, v105, v104
	v_cvt_f32_f16_e32 v104, v223
	v_mul_f32_e32 v105, 0xbfb8aa3b, v104
	v_exp_f32_e32 v105, v105
	s_nop 0
	v_add_f32_e32 v105, 1.0, v105
	v_div_scale_f32 v108, s[8:9], v105, v105, v104
	v_rcp_f32_e32 v109, v108
	s_nop 0
	v_fma_f32 v170, -v108, v109, 1.0
	v_fmac_f32_e32 v109, v170, v109
	v_div_scale_f32 v170, vcc, v104, v105, v104
	v_mul_f32_e32 v171, v170, v109
	v_fma_f32 v177, -v108, v171, v170
	v_fmac_f32_e32 v171, v177, v109
	v_fma_f32 v108, -v108, v171, v170
	v_div_fmas_f32 v108, v108, v109, v171
	v_div_fixup_f32 v177, v108, v105, v104
	v_mov_b32_e32 v104, v111
	v_mov_b32_e32 v105, v107
	v_pk_mul_f32 v[104:105], v[104:105], v[104:105]
	v_mov_b32_e32 v108, v103
	v_mov_b32_e32 v109, v99
	v_pk_mul_f32 v[108:109], v[108:109], v[108:109]
	v_mov_b32_e32 v170, v104
	v_mov_b32_e32 v171, v100
	v_mov_b32_e32 v100, v105
	v_pk_add_f32 v[100:101], v[170:171], v[100:101]
	v_mov_b32_e32 v104, v108
	v_mov_b32_e32 v105, v96
	v_pk_add_f32 v[100:101], v[100:101], v[104:105]
	v_mov_b32_e32 v96, v109
	v_pk_add_f32 v[96:97], v[100:101], v[96:97]
	s_nop 1
	v_mov_b32_dpp v101, v97 quad_perm:[1,0,3,2] row_mask:0xf bank_mask:0xf bound_ctrl:1
	v_mov_b32_dpp v100, v96 quad_perm:[1,0,3,2] row_mask:0xf bank_mask:0xf bound_ctrl:1
	v_pk_add_f32 v[96:97], v[96:97], v[100:101]
	s_nop 1
	v_mov_b32_dpp v101, v97 quad_perm:[2,3,0,1] row_mask:0xf bank_mask:0xf bound_ctrl:1
	v_mov_b32_dpp v100, v96 quad_perm:[2,3,0,1] row_mask:0xf bank_mask:0xf bound_ctrl:1
	v_pk_add_f32 v[96:97], v[96:97], v[100:101]
	s_nop 1
	v_mov_b32_dpp v101, v97 row_ror:4 row_mask:0xf bank_mask:0xf bound_ctrl:1
	v_mov_b32_dpp v100, v96 row_ror:4 row_mask:0xf bank_mask:0xf bound_ctrl:1
	v_pk_add_f32 v[96:97], v[96:97], v[100:101]
	s_nop 1
	v_mov_b32_dpp v101, v97 row_ror:8 row_mask:0xf bank_mask:0xf bound_ctrl:1
	v_mov_b32_dpp v100, v96 row_ror:8 row_mask:0xf bank_mask:0xf bound_ctrl:1
	v_pk_add_f32 v[96:97], v[96:97], v[100:101]
	s_nop 0
	v_pk_fma_f32 v[96:97], v[96:97], s[0:1], v[174:175] op_sel_hi:[1,0,0]
	s_nop 0
	v_mul_f32_e32 v100, 0x4b800000, v97
	v_cmp_gt_f32_e64 s[8:9], s49, v97
	v_cmp_gt_f32_e32 vcc, s49, v96
	s_nop 0
	v_cndmask_b32_e64 v97, v97, v100, s[8:9]
	v_rsq_f32_e32 v97, v97
	s_nop 0
	v_mul_f32_e32 v100, 0x45800000, v97
	v_cndmask_b32_e64 v97, v97, v100, s[8:9]
	v_mul_f32_e32 v100, v110, v97
	v_mul_f32_e32 v100, v234, v100
	v_mul_f32_e32 v100, v172, v100
	v_med3_f32 v100, v100, s57, v194
	v_cvt_f16_f32_e32 v100, v100
	global_store_short v[168:169], v100, off offset:768
	v_mul_f32_e32 v100, v106, v97
	v_mul_f32_e32 v100, v233, v100
	v_mul_f32_e32 v100, v173, v100
	v_med3_f32 v100, v100, s57, v194
	v_cvt_f16_f32_e32 v100, v100
	global_store_short v[168:169], v100, off offset:800
	v_mul_f32_e32 v100, v102, v97
	v_mul_f32_e32 v97, v98, v97
	v_mul_f32_e32 v97, v231, v97
	v_mul_f32_e32 v97, v177, v97
	v_med3_f32 v97, v97, s57, v194
	v_cvt_f16_f32_e32 v97, v97
	v_mul_f32_e32 v100, v232, v100
	v_mul_f32_e32 v100, v176, v100
	v_med3_f32 v100, v100, s57, v194
	global_store_short v[168:169], v97, off offset:864
	v_mul_f32_e32 v97, 0x4b800000, v96
	v_cndmask_b32_e32 v96, v96, v97, vcc
	v_rsq_f32_e32 v96, v96
	v_cvt_f16_f32_e32 v100, v100
	v_mul_f32_e32 v97, 0x45800000, v96
	v_cndmask_b32_e32 v96, v96, v97, vcc
	v_cvt_f32_f16_e32 v97, v181
	global_store_short v[168:169], v100, off offset:832
	v_mul_f32_e32 v98, v111, v96
	v_mul_f32_e32 v98, v234, v98
	v_mul_f32_e32 v100, 0xbfb8aa3b, v97
	v_exp_f32_e32 v100, v100
	s_nop 0
	v_add_f32_e32 v100, 1.0, v100
	v_div_scale_f32 v101, s[8:9], v100, v100, v97
	v_rcp_f32_e32 v102, v101
	s_nop 0
	v_fma_f32 v104, -v101, v102, 1.0
	v_fmac_f32_e32 v102, v104, v102
	v_div_scale_f32 v104, vcc, v97, v100, v97
	v_mul_f32_e32 v105, v104, v102
	v_fma_f32 v106, -v101, v105, v104
	v_fmac_f32_e32 v105, v106, v102
	v_fma_f32 v101, -v101, v105, v104
	v_div_fmas_f32 v101, v101, v102, v105
	v_div_fixup_f32 v97, v101, v100, v97
	v_mul_f32_e32 v97, v97, v98
	v_med3_f32 v97, v97, s57, v194
	v_cvt_f16_f32_e32 v97, v97
	v_mul_f32_e32 v98, v107, v96
	v_mul_f32_e32 v98, v233, v98
	global_store_short v[166:167], v97, off offset:3072
	v_cvt_f32_f16_e32 v97, v180
	v_mul_f32_e32 v100, 0xbfb8aa3b, v97
	v_exp_f32_e32 v100, v100
	s_nop 0
	v_add_f32_e32 v100, 1.0, v100
	v_div_scale_f32 v101, s[8:9], v100, v100, v97
	v_rcp_f32_e32 v102, v101
	s_nop 0
	v_fma_f32 v104, -v101, v102, 1.0
	v_fmac_f32_e32 v102, v104, v102
	v_div_scale_f32 v104, vcc, v97, v100, v97
	v_mul_f32_e32 v105, v104, v102
	v_fma_f32 v106, -v101, v105, v104
	v_fmac_f32_e32 v105, v106, v102
	v_fma_f32 v101, -v101, v105, v104
	v_div_fmas_f32 v101, v101, v102, v105
	v_div_fixup_f32 v97, v101, v100, v97
	v_mul_f32_e32 v97, v97, v98
	v_med3_f32 v97, v97, s57, v194
	v_cvt_f16_f32_e32 v97, v97
	v_mul_f32_e32 v98, v103, v96
	v_mul_f32_e32 v98, v232, v98
	v_mul_f32_e32 v96, v99, v96
	global_store_short v[166:167], v97, off offset:3104
	v_cvt_f32_f16_e32 v97, v179
	v_mul_f32_e32 v96, v231, v96
	v_mul_f32_e32 v100, 0xbfb8aa3b, v97
	v_exp_f32_e32 v100, v100
	s_nop 0
	v_add_f32_e32 v100, 1.0, v100
	v_div_scale_f32 v101, s[8:9], v100, v100, v97
	v_rcp_f32_e32 v102, v101
	s_nop 0
	v_fma_f32 v103, -v101, v102, 1.0
	v_fmac_f32_e32 v102, v103, v102
	v_div_scale_f32 v103, vcc, v97, v100, v97
	v_mul_f32_e32 v104, v103, v102
	v_fma_f32 v105, -v101, v104, v103
	v_fmac_f32_e32 v104, v105, v102
	v_fma_f32 v101, -v101, v104, v103
	v_div_fmas_f32 v101, v101, v102, v104
	v_div_fixup_f32 v97, v101, v100, v97
	v_mul_f32_e32 v97, v97, v98
	v_med3_f32 v97, v97, s57, v194
	v_cvt_f16_f32_e32 v97, v97
	global_store_short v[166:167], v97, off offset:3136
	v_cvt_f32_f16_e32 v97, v178
	v_mul_f32_e32 v98, 0xbfb8aa3b, v97
	v_exp_f32_e32 v98, v98
	s_nop 0
	v_add_f32_e32 v98, 1.0, v98
	v_div_scale_f32 v99, s[8:9], v98, v98, v97
	v_rcp_f32_e32 v100, v99
	s_nop 0
	v_fma_f32 v101, -v99, v100, 1.0
	v_fmac_f32_e32 v100, v101, v100
	v_div_scale_f32 v101, vcc, v97, v98, v97
	v_mul_f32_e32 v102, v101, v100
	v_fma_f32 v103, -v99, v102, v101
	v_fmac_f32_e32 v102, v103, v100
	v_fma_f32 v99, -v99, v102, v101
	v_div_fmas_f32 v99, v99, v100, v102
	v_div_fixup_f32 v97, v99, v98, v97
	v_mul_f32_e32 v96, v97, v96
	v_med3_f32 v96, v96, s57, v194
	v_cvt_f16_f32_e32 v96, v96
	s_andn2_b64 vcc, exec, s[10:11]
	global_store_short v[166:167], v96, off offset:3168
	ds_read_b128 v[96:99], v116 offset:55296
	ds_read_b128 v[240:243], v117 offset:36864
	ds_read_b128 v[244:247], v117 offset:39168
	ds_read_b128 v[252:255], v117 offset:41472
	s_waitcnt lgkmcnt(2)
	v_mfma_f32_16x16x32_f16 v[80:83], v[96:99], v[240:243], v[80:83]
	ds_read_b128 v[240:243], v117 offset:43776
	ds_read_b128 v[100:103], v116 offset:55360
	s_waitcnt lgkmcnt(3)
	v_mfma_f32_16x16x32_f16 v[84:87], v[96:99], v[244:247], v[84:87]
	ds_read_b128 v[244:247], v117 offset:36928
	s_waitcnt lgkmcnt(3)
	v_mfma_f32_16x16x32_f16 v[88:91], v[96:99], v[252:255], v[88:91]
	ds_read_b128 v[252:255], v117 offset:39232
	s_waitcnt lgkmcnt(3)
	v_mfma_f32_16x16x32_f16 v[92:95], v[96:99], v[240:243], v[92:95]
	ds_read_b128 v[240:243], v117 offset:41536
	s_waitcnt lgkmcnt(2)
	v_mfma_f32_16x16x32_f16 v[80:83], v[100:103], v[244:247], v[80:83]
	ds_read_b128 v[244:247], v117 offset:43840
	s_waitcnt lgkmcnt(2)
	v_mfma_f32_16x16x32_f16 v[84:87], v[100:103], v[252:255], v[84:87]
	s_waitcnt lgkmcnt(1)
	v_mfma_f32_16x16x32_f16 v[88:91], v[100:103], v[240:243], v[88:91]
	s_waitcnt lgkmcnt(0)
	s_barrier
	v_mfma_f32_16x16x32_f16 v[92:95], v[100:103], v[244:247], v[92:95]
	v_max_f32_e32 v96, v80, v80
	v_med3_f32 v96, v96, s57, v194
	v_cvt_f16_f32_e32 v96, v96
	ds_write_b16 v215, v96 offset:46080
	v_max_f32_e32 v96, v81, v81
	v_med3_f32 v96, v96, s57, v194
	v_cvt_f16_f32_e32 v96, v96
	ds_write_b16 v215, v96 offset:46224
	v_max_f32_e32 v96, v82, v82
	v_med3_f32 v96, v96, s57, v194
	v_cvt_f16_f32_e32 v96, v96
	ds_write_b16 v215, v96 offset:46368
	v_max_f32_e32 v96, v83, v83
	v_med3_f32 v96, v96, s57, v194
	v_cvt_f16_f32_e32 v96, v96
	ds_write_b16 v215, v96 offset:46512
	v_max_f32_e32 v96, v84, v84
	v_med3_f32 v96, v96, s57, v194
	v_cvt_f16_f32_e32 v96, v96
	ds_write_b16 v215, v96 offset:46112
	v_max_f32_e32 v96, v85, v85
	v_med3_f32 v96, v96, s57, v194
	v_cvt_f16_f32_e32 v96, v96
	ds_write_b16 v216, v96 offset:46224
	v_max_f32_e32 v96, v86, v86
	v_med3_f32 v96, v96, s57, v194
	v_cvt_f16_f32_e32 v96, v96
	ds_write_b16 v216, v96 offset:46368
	v_max_f32_e32 v96, v87, v87
	v_med3_f32 v96, v96, s57, v194
	v_cvt_f16_f32_e32 v96, v96
	ds_write_b16 v216, v96 offset:46512
	v_max_f32_e32 v96, v88, v88
	v_med3_f32 v96, v96, s57, v194
	v_cvt_f16_f32_e32 v96, v96
	ds_write_b16 v215, v96 offset:46144
	v_max_f32_e32 v96, v89, v89
	v_med3_f32 v96, v96, s57, v194
	v_cvt_f16_f32_e32 v96, v96
	ds_write_b16 v217, v96 offset:46224
	v_max_f32_e32 v96, v90, v90
	v_med3_f32 v96, v96, s57, v194
	v_cvt_f16_f32_e32 v96, v96
	ds_write_b16 v217, v96 offset:46368
	v_max_f32_e32 v96, v91, v91
	v_med3_f32 v96, v96, s57, v194
	v_cvt_f16_f32_e32 v96, v96
	ds_write_b16 v217, v96 offset:46512
	v_max_f32_e32 v96, v92, v92
	v_med3_f32 v96, v96, s57, v194
	v_cvt_f16_f32_e32 v96, v96
	ds_write_b16 v215, v96 offset:46176
	v_max_f32_e32 v96, v93, v93
	v_med3_f32 v96, v96, s57, v194
	v_cvt_f16_f32_e32 v96, v96
	ds_write_b16 v218, v96 offset:46224
	v_max_f32_e32 v96, v94, v94
	v_med3_f32 v96, v96, s57, v194
	v_cvt_f16_f32_e32 v96, v96
	ds_write_b16 v218, v96 offset:46368
	v_max_f32_e32 v96, v95, v95
	v_med3_f32 v96, v96, s57, v194
	v_cvt_f16_f32_e32 v96, v96
	ds_write_b16 v218, v96 offset:46512
	ds_write_b128 v220, v[16:19]
	ds_write_b128 v211, v[20:23]
	ds_write_b128 v221, v[24:27]
	ds_write_b128 v212, v[28:31]
	ds_write_b128 v222, v[32:35]
	ds_write_b128 v213, v[36:39]
	s_waitcnt lgkmcnt(0)
	s_cbranch_vccnz .LBB0_525
	v_add_co_u32_e32 v0, vcc, 0xc81e000, v164
	s_nop 1
	v_addc_co_u32_e32 v1, vcc, 0, v165, vcc
	v_add_co_u32_e32 v4, vcc, 0xc81e000, v162
	s_nop 1
	v_addc_co_u32_e32 v5, vcc, 0, v163, vcc
	v_add_co_u32_e32 v8, vcc, 0xc81e000, v160
	global_load_dwordx4 v[0:3], v[0:1], off
	s_nop 0
	global_load_dwordx4 v[4:7], v[4:5], off
	v_addc_co_u32_e32 v9, vcc, 0, v161, vcc
	v_add_co_u32_e32 v12, vcc, 0xc81e000, v158
	s_nop 1
	v_addc_co_u32_e32 v13, vcc, 0, v159, vcc
	v_add_co_u32_e32 v16, vcc, 0xc81e000, v156
	global_load_dwordx4 v[8:11], v[8:9], off
	s_nop 0
	global_load_dwordx4 v[12:15], v[12:13], off
	v_addc_co_u32_e32 v17, vcc, 0, v157, vcc
	v_add_co_u32_e32 v20, vcc, 0xc81e000, v154
	s_nop 1
	v_addc_co_u32_e32 v21, vcc, 0, v155, vcc
	v_add_co_u32_e32 v24, vcc, 0xc81e000, v152
	global_load_dwordx4 v[16:19], v[16:17], off
	s_nop 0
	global_load_dwordx4 v[20:23], v[20:21], off
	v_addc_co_u32_e32 v25, vcc, 0, v153, vcc
	v_add_co_u32_e32 v28, vcc, 0xc81e000, v150
	s_nop 1
	v_addc_co_u32_e32 v29, vcc, 0, v151, vcc
	v_add_co_u32_e32 v32, vcc, 0xc81e000, v148
	global_load_dwordx4 v[24:27], v[24:25], off
	s_nop 0
	global_load_dwordx4 v[28:31], v[28:29], off
	v_addc_co_u32_e32 v33, vcc, 0, v149, vcc
	v_add_co_u32_e32 v36, vcc, 0xc81e000, v146
	s_nop 1
	v_addc_co_u32_e32 v37, vcc, 0, v147, vcc
	global_load_dwordx4 v[32:35], v[32:33], off
	s_nop 0
	global_load_dwordx4 v[36:39], v[36:37], off
.LBB0_525:
	v_lshl_add_u64 v[108:109], v[142:143], 0, v[140:141]
	v_add_co_u32_e32 v96, vcc, 0x65000, v108
	global_load_dword v112, v192, s[12:13] offset:4 sc1
	s_nop 0
	v_addc_co_u32_e32 v97, vcc, 0, v109, vcc
	global_load_ushort v238, v[96:97], off offset:256
	global_load_ushort v237, v[96:97], off offset:288
	global_load_ushort v236, v[96:97], off offset:320
	global_load_ushort v235, v[96:97], off offset:352
	v_add_co_u32_e32 v96, vcc, 0x66000, v108
	s_cmpk_lt_u32 s14, 0x7f
	s_nop 0
	v_addc_co_u32_e32 v97, vcc, 0, v109, vcc
	global_load_ushort v234, v[96:97], off offset:2560
	global_load_ushort v233, v[96:97], off offset:2592
	global_load_ushort v232, v[96:97], off offset:2624
	global_load_ushort v231, v[96:97], off offset:2656
	v_add_co_u32_e32 v96, vcc, 0x68000, v108
	s_cselect_b64 s[10:11], -1, 0
	s_nop 0
	v_addc_co_u32_e32 v97, vcc, 0, v109, vcc
	global_load_ushort v230, v[96:97], off offset:768
	global_load_ushort v229, v[96:97], off offset:800
	global_load_ushort v228, v[96:97], off offset:832
	global_load_ushort v227, v[96:97], off offset:864
	v_add_co_u32_e32 v96, vcc, 0x69000, v108
	s_cmpk_gt_u32 s14, 0x7e
	s_nop 0
	v_addc_co_u32_e32 v97, vcc, 0, v109, vcc
	global_load_ushort v226, v[96:97], off offset:3072
	global_load_ushort v225, v[96:97], off offset:3104
	global_load_ushort v224, v[96:97], off offset:3136
	global_load_ushort v223, v[96:97], off offset:3168
	ds_read_b64 v[110:111], v214 offset:9216
	ds_read_b128 v[146:149], v116 offset:46080
	ds_read_b128 v[240:243], v117
	ds_read_b128 v[244:247], v117 offset:2304
	ds_read_b128 v[252:255], v117 offset:4608
	s_waitcnt lgkmcnt(2)
	v_mfma_f32_16x16x32_f16 v[154:157], v[146:149], v[240:243], 0
	ds_read_b128 v[240:243], v117 offset:6912
	ds_read_b128 v[150:153], v116 offset:46144
	s_waitcnt lgkmcnt(3)
	v_mfma_f32_16x16x32_f16 v[104:107], v[146:149], v[244:247], 0
	ds_read_b128 v[244:247], v117 offset:64
	s_waitcnt lgkmcnt(3)
	v_mfma_f32_16x16x32_f16 v[100:103], v[146:149], v[252:255], 0
	ds_read_b128 v[252:255], v117 offset:2368
	s_waitcnt lgkmcnt(3)
	v_mfma_f32_16x16x32_f16 v[96:99], v[146:149], v[240:243], 0
	ds_read_b128 v[240:243], v117 offset:4672
	s_waitcnt lgkmcnt(2)
	v_mfma_f32_16x16x32_f16 v[154:157], v[150:153], v[244:247], v[154:157]
	ds_read_b128 v[244:247], v117 offset:6976
	s_waitcnt lgkmcnt(2)
	v_mfma_f32_16x16x32_f16 v[104:107], v[150:153], v[252:255], v[104:107]
	s_waitcnt lgkmcnt(1)
	v_mfma_f32_16x16x32_f16 v[100:103], v[150:153], v[240:243], v[100:103]
	s_waitcnt lgkmcnt(0)
	v_mfma_f32_16x16x32_f16 v[96:99], v[150:153], v[244:247], v[96:99]
	v_cvt_f32_f16_e32 v146, v110
	v_cvt_f32_f16_sdwa v110, v110 dst_sel:DWORD dst_unused:UNUSED_PAD src0_sel:WORD_1
	v_sub_f32_e32 v146, v146, v154
	v_sub_f32_e32 v110, v110, v155
	v_med3_f32 v110, v110, s57, v194
	v_cvt_f16_f32_e32 v110, v110
	v_med3_f32 v146, v146, s57, v194
	v_cvt_f16_f32_e32 v146, v146
	ds_write_b16 v215, v110 offset:55440
	v_cvt_f32_f16_e32 v110, v111
	ds_write_b16 v215, v146 offset:55296
	v_sub_f32_e32 v110, v110, v156
	v_med3_f32 v110, v110, s57, v194
	v_cvt_f16_f32_e32 v110, v110
	ds_write_b16 v215, v110 offset:55584
	v_cvt_f32_f16_sdwa v110, v111 dst_sel:DWORD dst_unused:UNUSED_PAD src0_sel:WORD_1
	v_sub_f32_e32 v110, v110, v157
	v_med3_f32 v110, v110, s57, v194
	v_cvt_f16_f32_e32 v110, v110
	ds_write_b16 v215, v110 offset:55728
	ds_read_b64 v[110:111], v214 offset:11520
	s_waitcnt lgkmcnt(0)
	v_cvt_f32_f16_e32 v146, v110
	v_sub_f32_e32 v104, v146, v104
	v_med3_f32 v104, v104, s57, v194
	v_cvt_f16_f32_e32 v104, v104
	ds_write_b16 v215, v104 offset:55328
	v_cvt_f32_f16_sdwa v104, v110 dst_sel:DWORD dst_unused:UNUSED_PAD src0_sel:WORD_1
	v_sub_f32_e32 v104, v104, v105
	v_med3_f32 v104, v104, s57, v194
	v_cvt_f16_f32_e32 v104, v104
	ds_write_b16 v216, v104 offset:55440
	v_cvt_f32_f16_e32 v104, v111
	v_sub_f32_e32 v104, v104, v106
	v_med3_f32 v104, v104, s57, v194
	v_cvt_f16_f32_e32 v104, v104
	ds_write_b16 v216, v104 offset:55584
	v_cvt_f32_f16_sdwa v104, v111 dst_sel:DWORD dst_unused:UNUSED_PAD src0_sel:WORD_1
	v_sub_f32_e32 v104, v104, v107
	v_med3_f32 v104, v104, s57, v194
	v_cvt_f16_f32_e32 v104, v104
	ds_write_b16 v216, v104 offset:55728
	ds_read_b64 v[104:105], v214 offset:13824
	s_waitcnt lgkmcnt(0)
	v_cvt_f32_f16_e32 v106, v104
	v_sub_f32_e32 v100, v106, v100
	v_med3_f32 v100, v100, s57, v194
	v_cvt_f16_f32_e32 v100, v100
	ds_write_b16 v215, v100 offset:55360
	v_cvt_f32_f16_sdwa v100, v104 dst_sel:DWORD dst_unused:UNUSED_PAD src0_sel:WORD_1
	v_sub_f32_e32 v100, v100, v101
	v_med3_f32 v100, v100, s57, v194
	v_cvt_f16_f32_e32 v100, v100
	ds_write_b16 v217, v100 offset:55440
	v_cvt_f32_f16_e32 v100, v105
	v_sub_f32_e32 v100, v100, v102
	v_med3_f32 v100, v100, s57, v194
	v_cvt_f16_f32_e32 v100, v100
	ds_write_b16 v217, v100 offset:55584
	v_cvt_f32_f16_sdwa v100, v105 dst_sel:DWORD dst_unused:UNUSED_PAD src0_sel:WORD_1
	v_sub_f32_e32 v100, v100, v103
	v_med3_f32 v100, v100, s57, v194
	v_cvt_f16_f32_e32 v100, v100
	ds_write_b16 v217, v100 offset:55728
	ds_read_b64 v[100:101], v214 offset:16128
	s_waitcnt lgkmcnt(0)
	v_cvt_f32_f16_e32 v102, v100
	v_sub_f32_e32 v96, v102, v96
	v_med3_f32 v96, v96, s57, v194
	v_cvt_f16_f32_e32 v96, v96
	ds_write_b16 v215, v96 offset:55392
	v_cvt_f32_f16_sdwa v96, v100 dst_sel:DWORD dst_unused:UNUSED_PAD src0_sel:WORD_1
	v_sub_f32_e32 v96, v96, v97
	v_med3_f32 v96, v96, s57, v194
	v_cvt_f16_f32_e32 v96, v96
	ds_write_b16 v218, v96 offset:55440
	v_cvt_f32_f16_e32 v96, v101
	v_sub_f32_e32 v96, v96, v98
	v_med3_f32 v96, v96, s57, v194
	v_cvt_f16_f32_e32 v96, v96
	ds_write_b16 v218, v96 offset:55584
	v_cvt_f32_f16_sdwa v96, v101 dst_sel:DWORD dst_unused:UNUSED_PAD src0_sel:WORD_1
	v_sub_f32_e32 v96, v96, v99
	v_med3_f32 v96, v96, s57, v194
	v_cvt_f16_f32_e32 v96, v96
	ds_write_b16 v218, v96 offset:55728
	s_waitcnt lgkmcnt(0)
	s_barrier
	s_cbranch_scc1 .LBB0_527
	ds_write_b128 v115, v[40:43]
	ds_write_b128 v209, v[44:47]
	ds_write_b128 v219, v[48:51]
	ds_write_b128 v210, v[52:55]
.LBB0_527:
	s_mov_b64 s[8:9], 0x65100
	v_lshl_add_u64 v[178:179], v[108:109], 0, s[8:9]
	s_mov_b64 s[8:9], 0x65120
	v_lshl_add_u64 v[176:177], v[108:109], 0, s[8:9]
	s_mov_b64 s[8:9], 0x65140
	v_lshl_add_u64 v[174:175], v[108:109], 0, s[8:9]
	s_mov_b64 s[8:9], 0x65160
	v_lshl_add_u64 v[172:173], v[108:109], 0, s[8:9]
	s_mov_b64 s[8:9], 0x66a00
	v_lshl_add_u64 v[168:169], v[108:109], 0, s[8:9]
	s_mov_b64 s[8:9], 0x66a20
	v_lshl_add_u64 v[166:167], v[108:109], 0, s[8:9]
	s_mov_b64 s[8:9], 0x66a40
	v_lshl_add_u64 v[164:165], v[108:109], 0, s[8:9]
	s_mov_b64 s[8:9], 0x66a60
	v_lshl_add_u64 v[162:163], v[108:109], 0, s[8:9]
	s_mov_b64 s[8:9], 0x68300
	v_lshl_add_u64 v[160:161], v[108:109], 0, s[8:9]
	s_mov_b64 s[8:9], 0x68320
	v_lshl_add_u64 v[158:159], v[108:109], 0, s[8:9]
	s_mov_b64 s[8:9], 0x68340
	v_lshl_add_u64 v[156:157], v[108:109], 0, s[8:9]
	s_mov_b64 s[8:9], 0x68360
	v_lshl_add_u64 v[154:155], v[108:109], 0, s[8:9]
	s_mov_b64 s[8:9], 0x69c00
	v_lshl_add_u64 v[152:153], v[108:109], 0, s[8:9]
	s_mov_b64 s[8:9], 0x69c20
	v_lshl_add_u64 v[150:151], v[108:109], 0, s[8:9]
	s_mov_b64 s[8:9], 0x69c40
	v_lshl_add_u64 v[148:149], v[108:109], 0, s[8:9]
	s_mov_b64 s[8:9], 0x69c60
	v_lshl_add_u64 v[146:147], v[108:109], 0, s[8:9]
	s_waitcnt vmcnt(15)
	v_cvt_f32_f16_e32 v239, v238
	s_mov_b32 s0, 0x358637bd
	v_pk_mul_f32 v[82:83], v[82:83], v[112:113] op_sel_hi:[1,0]
	v_mul_f32_e64 v80, v80, v112
	v_mul_f32_e64 v81, v81, v112
	v_pk_mul_f32 v[86:87], v[86:87], v[112:113] op_sel_hi:[1,0]
	v_pk_mul_f32 v[84:85], v[84:85], v[112:113] op_sel_hi:[1,0]
	v_mul_f32_e64 v90, v90, v112
	v_mul_f32_e64 v91, v91, v112
	v_pk_mul_f32 v[88:89], v[88:89], v[112:113] op_sel_hi:[1,0]
	v_pk_mul_f32 v[94:95], v[94:95], v[112:113] op_sel_hi:[1,0]
	v_pk_mul_f32 v[92:93], v[92:93], v[112:113] op_sel_hi:[1,0]
	global_load_dword v238, v[118:119], off
	ds_read_b128 v[240:243], v116 offset:27648
	ds_read_b128 v[244:247], v117 offset:46080
	ds_read_b128 v[252:255], v117 offset:48384
	s_waitcnt lgkmcnt(1)
	v_mfma_f32_16x16x32_f16 v[108:111], v[240:243], v[244:247], 0
	ds_read_b128 v[244:247], v117 offset:50688
	s_waitcnt lgkmcnt(1)
	v_mfma_f32_16x16x32_f16 v[104:107], v[240:243], v[252:255], 0
	ds_read_b128 v[252:255], v117 offset:52992
	s_waitcnt lgkmcnt(1)
	v_mfma_f32_16x16x32_f16 v[100:103], v[240:243], v[244:247], 0
	s_waitcnt lgkmcnt(0)
	v_mfma_f32_16x16x32_f16 v[96:99], v[240:243], v[252:255], 0
	ds_read_b128 v[240:243], v116 offset:27712
	ds_read_b128 v[244:247], v117 offset:46144
	ds_read_b128 v[252:255], v117 offset:48448
	s_waitcnt lgkmcnt(1)
	v_mfma_f32_16x16x32_f16 v[108:111], v[240:243], v[244:247], v[108:111]
	ds_read_b128 v[244:247], v117 offset:50752
	s_waitcnt lgkmcnt(1)
	v_mfma_f32_16x16x32_f16 v[104:107], v[240:243], v[252:255], v[104:107]
	ds_read_b128 v[252:255], v117 offset:53056
	s_waitcnt lgkmcnt(1)
	v_mfma_f32_16x16x32_f16 v[100:103], v[240:243], v[244:247], v[100:103]
	s_waitcnt lgkmcnt(0)
	v_mfma_f32_16x16x32_f16 v[96:99], v[240:243], v[252:255], v[96:99]
	ds_read_b128 v[240:243], v116 offset:18432
	ds_read_b128 v[244:247], v117 offset:55296
	ds_read_b128 v[252:255], v117 offset:57600
	s_waitcnt lgkmcnt(1)
	v_mfma_f32_16x16x32_f16 v[108:111], v[240:243], v[244:247], v[108:111]
	ds_read_b128 v[244:247], v117 offset:59904
	s_waitcnt lgkmcnt(1)
	v_mfma_f32_16x16x32_f16 v[104:107], v[240:243], v[252:255], v[104:107]
	ds_read_b128 v[252:255], v117 offset:62208
	s_waitcnt lgkmcnt(1)
	v_mfma_f32_16x16x32_f16 v[100:103], v[240:243], v[244:247], v[100:103]
	s_waitcnt lgkmcnt(0)
	v_mfma_f32_16x16x32_f16 v[96:99], v[240:243], v[252:255], v[96:99]
	ds_read_b128 v[240:243], v116 offset:18496
	ds_read_b128 v[244:247], v117 offset:55360
	ds_read_b128 v[252:255], v117 offset:57664
	s_waitcnt lgkmcnt(1)
	v_mfma_f32_16x16x32_f16 v[108:111], v[240:243], v[244:247], v[108:111]
	ds_read_b128 v[244:247], v117 offset:59968
	s_waitcnt lgkmcnt(1)
	v_mfma_f32_16x16x32_f16 v[104:107], v[240:243], v[252:255], v[104:107]
	s_nop 7
	v_mov_b32_e32 v170, v108
	v_mov_b32_e32 v171, v104
	ds_read_b128 v[252:255], v117 offset:62272
	s_waitcnt lgkmcnt(1)
	v_mfma_f32_16x16x32_f16 v[100:103], v[240:243], v[244:247], v[100:103]
	s_nop 7
	v_mul_f32_e64 v180, v170, v170
	v_mul_f32_e64 v181, v171, v171
	s_waitcnt lgkmcnt(0)
	v_mfma_f32_16x16x32_f16 v[96:99], v[240:243], v[252:255], v[96:99]
	v_mul_f32_e32 v240, 0xbfb8aa3b, v239
	v_exp_f32_e32 v240, v240
	v_mov_b32_e32 v170, v100
	s_nop 4
	v_mov_b32_e32 v171, v96
	v_pk_mul_f32 v[170:171], v[170:171], v[170:171]
	v_add_f32_e32 v240, 1.0, v240
	v_div_scale_f32 v241, s[8:9], v240, v240, v239
	v_rcp_f32_e32 v242, v241
	s_nop 0
	v_fma_f32 v243, -v241, v242, 1.0
	v_fmac_f32_e32 v242, v243, v242
	v_div_scale_f32 v243, vcc, v239, v240, v239
	v_mul_f32_e32 v244, v243, v242
	v_fma_f32 v245, -v241, v244, v243
	v_fmac_f32_e32 v244, v245, v242
	v_fma_f32 v241, -v241, v244, v243
	v_div_fmas_f32 v241, v241, v242, v244
	v_div_fixup_f32 v239, v241, v240, v239
	s_waitcnt vmcnt(15)
	v_cvt_f32_f16_e32 v240, v237
	global_load_dword v237, v[118:119], off offset:64
	v_mul_f32_e32 v241, 0xbfb8aa3b, v240
	v_exp_f32_e32 v241, v241
	s_nop 0
	v_add_f32_e32 v241, 1.0, v241
	v_div_scale_f32 v242, s[8:9], v241, v241, v240
	v_rcp_f32_e32 v243, v242
	s_nop 0
	v_fma_f32 v244, -v242, v243, 1.0
	v_fmac_f32_e32 v243, v244, v243
	v_div_scale_f32 v244, vcc, v240, v241, v240
	v_mul_f32_e32 v245, v244, v243
	v_fma_f32 v246, -v242, v245, v244
	v_fmac_f32_e32 v245, v246, v243
	v_fma_f32 v242, -v242, v245, v244
	v_div_fmas_f32 v242, v242, v243, v245
	v_div_fixup_f32 v246, v242, v241, v240
	s_waitcnt vmcnt(15)
	v_cvt_f32_f16_e32 v240, v236
	global_load_dword v236, v[118:119], off offset:128
	v_mul_f32_e32 v241, 0xbfb8aa3b, v240
	v_exp_f32_e32 v241, v241
	s_nop 0
	v_add_f32_e32 v241, 1.0, v241
	v_div_scale_f32 v242, s[8:9], v241, v241, v240
	v_rcp_f32_e32 v243, v242
	s_nop 0
	v_fma_f32 v244, -v242, v243, 1.0
	v_fmac_f32_e32 v243, v244, v243
	v_div_scale_f32 v244, vcc, v240, v241, v240
	v_mul_f32_e32 v245, v244, v243
	v_fma_f32 v247, -v242, v245, v244
	v_fmac_f32_e32 v245, v247, v243
	v_fma_f32 v242, -v242, v245, v244
	v_div_fmas_f32 v242, v242, v243, v245
	v_div_fixup_f32 v247, v242, v241, v240
	s_waitcnt vmcnt(15)
	v_cvt_f32_f16_e32 v240, v235
	global_load_dword v235, v[118:119], off offset:192
	v_mul_f32_e32 v241, 0xbfb8aa3b, v240
	v_exp_f32_e32 v241, v241
	s_nop 0
	v_add_f32_e32 v241, 1.0, v241
	v_div_scale_f32 v242, s[8:9], v241, v241, v240
	v_rcp_f32_e32 v243, v242
	s_nop 0
	v_fma_f32 v244, -v242, v243, 1.0
	v_fmac_f32_e32 v243, v244, v243
	v_div_scale_f32 v244, vcc, v240, v241, v240
	v_mul_f32_e32 v245, v244, v243
	v_fma_f32 v248, -v242, v245, v244
	v_fmac_f32_e32 v245, v248, v243
	v_fma_f32 v242, -v242, v245, v244
	v_div_fmas_f32 v242, v242, v243, v245
	v_div_fixup_f32 v248, v242, v241, v240
	v_mov_b32_e32 v240, v109
	v_mov_b32_e32 v241, v105
	v_pk_mul_f32 v[240:241], v[240:241], v[240:241]
	v_mov_b32_e32 v242, v101
	v_mov_b32_e32 v243, v97
	v_pk_mul_f32 v[242:243], v[242:243], v[242:243]
	v_mov_b32_e32 v244, v240
	v_mov_b32_e32 v245, v180
	v_mov_b32_e32 v180, v241
	v_pk_add_f32 v[180:181], v[244:245], v[180:181]
	v_mov_b32_e32 v240, v242
	v_mov_b32_e32 v241, v170
	v_pk_add_f32 v[180:181], v[180:181], v[240:241]
	v_mov_b32_e32 v170, v243
	v_pk_add_f32 v[170:171], v[180:181], v[170:171]
	s_nop 1
	v_mov_b32_dpp v181, v171 quad_perm:[1,0,3,2] row_mask:0xf bank_mask:0xf bound_ctrl:1
	v_mov_b32_dpp v180, v170 quad_perm:[1,0,3,2] row_mask:0xf bank_mask:0xf bound_ctrl:1
	v_pk_add_f32 v[170:171], v[170:171], v[180:181]
	s_nop 1
	v_mov_b32_dpp v181, v171 quad_perm:[2,3,0,1] row_mask:0xf bank_mask:0xf bound_ctrl:1
	v_mov_b32_dpp v180, v170 quad_perm:[2,3,0,1] row_mask:0xf bank_mask:0xf bound_ctrl:1
	v_pk_add_f32 v[170:171], v[170:171], v[180:181]
	s_nop 1
	v_mov_b32_dpp v181, v171 row_ror:4 row_mask:0xf bank_mask:0xf bound_ctrl:1
	v_mov_b32_dpp v180, v170 row_ror:4 row_mask:0xf bank_mask:0xf bound_ctrl:1
	v_pk_add_f32 v[170:171], v[170:171], v[180:181]
	s_nop 1
	v_mov_b32_dpp v181, v171 row_ror:8 row_mask:0xf bank_mask:0xf bound_ctrl:1
	v_mov_b32_dpp v180, v170 row_ror:8 row_mask:0xf bank_mask:0xf bound_ctrl:1
	v_pk_add_f32 v[180:181], v[170:171], v[180:181]
	v_mov_b64_e32 v[170:171], s[0:1]
	s_mov_b32 s0, 0x3c800000
	v_pk_fma_f32 v[180:181], v[180:181], s[0:1], v[170:171] op_sel_hi:[1,0,0]
	s_nop 0
	v_mul_f32_e32 v240, 0x4b800000, v181
	v_cmp_gt_f32_e64 s[8:9], s49, v181
	v_cmp_gt_f32_e32 vcc, s49, v180
	s_nop 0
	v_cndmask_b32_e64 v181, v181, v240, s[8:9]
	v_rsq_f32_e32 v181, v181
	s_nop 0
	v_mul_f32_e32 v240, 0x45800000, v181
	v_cndmask_b32_e64 v181, v181, v240, s[8:9]
	v_mul_f32_e32 v96, v96, v181
	v_mul_f32_e32 v100, v100, v181
	s_waitcnt vmcnt(1)
	v_mul_f32_e32 v100, v236, v100
	v_mul_f32_e32 v100, v247, v100
	v_med3_f32 v100, v100, s57, v194
	s_waitcnt vmcnt(0)
	v_mul_f32_e32 v96, v235, v96
	v_mul_f32_e32 v96, v248, v96
	v_med3_f32 v96, v96, s57, v194
	v_cvt_f16_f32_e32 v96, v96
	v_cvt_f16_f32_e32 v100, v100
	v_mul_f32_e32 v108, v108, v181
	v_mul_f32_e32 v108, v238, v108
	global_store_short v[172:173], v96, off
	v_mul_f32_e32 v96, 0x4b800000, v180
	v_cndmask_b32_e32 v96, v180, v96, vcc
	v_rsq_f32_e32 v96, v96
	v_mul_f32_e32 v108, v239, v108
	v_med3_f32 v108, v108, s57, v194
	global_store_short v[174:175], v100, off
	v_mul_f32_e32 v100, 0x45800000, v96
	v_cvt_f16_f32_e32 v108, v108
	v_cndmask_b32_e32 v96, v96, v100, vcc
	v_cvt_f32_f16_e32 v100, v234
	v_mul_f32_e32 v104, v104, v181
	v_mul_f32_e32 v104, v237, v104
	global_store_short v[178:179], v108, off
	v_mul_f32_e32 v104, v246, v104
	v_mul_f32_e32 v108, 0xbfb8aa3b, v100
	v_med3_f32 v104, v104, s57, v194
	v_exp_f32_e32 v108, v108
	v_cvt_f16_f32_e32 v104, v104
	v_mul_f32_e32 v101, v101, v96
	v_mul_f32_e32 v101, v236, v101
	v_add_f32_e32 v108, 1.0, v108
	global_store_short v[176:177], v104, off
	v_mul_f32_e32 v104, v109, v96
	v_div_scale_f32 v109, s[8:9], v108, v108, v100
	v_rcp_f32_e32 v172, v109
	v_mul_f32_e32 v104, v238, v104
	v_fma_f32 v173, -v109, v172, 1.0
	v_fmac_f32_e32 v172, v173, v172
	v_div_scale_f32 v173, vcc, v100, v108, v100
	v_mul_f32_e32 v174, v173, v172
	v_fma_f32 v175, -v109, v174, v173
	v_fmac_f32_e32 v174, v175, v172
	v_fma_f32 v109, -v109, v174, v173
	v_div_fmas_f32 v109, v109, v172, v174
	v_div_fixup_f32 v100, v109, v108, v100
	v_mul_f32_e32 v100, v100, v104
	v_med3_f32 v100, v100, s57, v194
	v_cvt_f16_f32_e32 v100, v100
	v_mul_f32_e32 v104, v105, v96
	v_mul_f32_e32 v104, v237, v104
	v_mul_f32_e32 v96, v97, v96
	global_store_short v[168:169], v100, off
	v_cvt_f32_f16_e32 v100, v233
	v_mul_f32_e32 v96, v235, v96
	v_mul_f32_e32 v105, 0xbfb8aa3b, v100
	v_exp_f32_e32 v105, v105
	s_nop 0
	v_add_f32_e32 v105, 1.0, v105
	v_div_scale_f32 v108, s[8:9], v105, v105, v100
	v_rcp_f32_e32 v109, v108
	s_nop 0
	v_fma_f32 v168, -v108, v109, 1.0
	v_fmac_f32_e32 v109, v168, v109
	v_div_scale_f32 v168, vcc, v100, v105, v100
	v_mul_f32_e32 v169, v168, v109
	v_fma_f32 v172, -v108, v169, v168
	v_fmac_f32_e32 v169, v172, v109
	v_fma_f32 v108, -v108, v169, v168
	v_div_fmas_f32 v108, v108, v109, v169
	v_div_fixup_f32 v100, v108, v105, v100
	v_mul_f32_e32 v100, v100, v104
	v_med3_f32 v100, v100, s57, v194
	v_cvt_f16_f32_e32 v100, v100
	global_store_short v[166:167], v100, off
	v_cvt_f32_f16_e32 v100, v232
	v_mul_f32_e32 v104, 0xbfb8aa3b, v100
	v_exp_f32_e32 v104, v104
	s_nop 0
	v_add_f32_e32 v104, 1.0, v104
	v_div_scale_f32 v105, s[8:9], v104, v104, v100
	v_rcp_f32_e32 v108, v105
	s_nop 0
	v_fma_f32 v109, -v105, v108, 1.0
	v_fmac_f32_e32 v108, v109, v108
	v_div_scale_f32 v109, vcc, v100, v104, v100
	v_mul_f32_e32 v166, v109, v108
	v_fma_f32 v167, -v105, v166, v109
	v_fmac_f32_e32 v166, v167, v108
	v_fma_f32 v105, -v105, v166, v109
	v_div_fmas_f32 v105, v105, v108, v166
	v_div_fixup_f32 v100, v105, v104, v100
	v_mul_f32_e32 v100, v100, v101
	v_med3_f32 v100, v100, s57, v194
	v_cvt_f16_f32_e32 v100, v100
	global_store_short v[164:165], v100, off
	v_cvt_f32_f16_e32 v100, v231
	v_mul_f32_e32 v97, 0xbfb8aa3b, v100
	v_exp_f32_e32 v97, v97
	s_nop 0
	v_add_f32_e32 v97, 1.0, v97
	v_div_scale_f32 v101, s[8:9], v97, v97, v100
	v_rcp_f32_e32 v104, v101
	s_nop 0
	v_fma_f32 v105, -v101, v104, 1.0
	v_fmac_f32_e32 v104, v105, v104
	v_div_scale_f32 v105, vcc, v100, v97, v100
	v_mul_f32_e32 v108, v105, v104
	v_fma_f32 v109, -v101, v108, v105
	v_fmac_f32_e32 v108, v109, v104
	v_fma_f32 v101, -v101, v108, v105
	v_div_fmas_f32 v101, v101, v104, v108
	v_cvt_f32_f16_e32 v104, v230
	v_div_fixup_f32 v97, v101, v97, v100
	v_mul_f32_e32 v96, v97, v96
	v_med3_f32 v96, v96, s57, v194
	v_mul_f32_e32 v105, 0xbfb8aa3b, v104
	v_exp_f32_e32 v105, v105
	v_cvt_f16_f32_e32 v96, v96
	v_mov_b32_e32 v97, v106
	v_add_f32_e32 v105, 1.0, v105
	v_div_scale_f32 v108, s[8:9], v105, v105, v104
	v_rcp_f32_e32 v109, v108
	global_store_short v[162:163], v96, off
	v_mov_b32_e32 v96, v110
	v_pk_mul_f32 v[100:101], v[96:97], v[96:97]
	v_fma_f32 v162, -v108, v109, 1.0
	v_fmac_f32_e32 v109, v162, v109
	v_div_scale_f32 v162, vcc, v104, v105, v104
	v_mul_f32_e32 v163, v162, v109
	v_fma_f32 v164, -v108, v163, v162
	v_fmac_f32_e32 v163, v164, v109
	v_fma_f32 v108, -v108, v163, v162
	v_div_fmas_f32 v108, v108, v109, v163
	v_div_fixup_f32 v164, v108, v105, v104
	v_cvt_f32_f16_e32 v104, v229
	v_mov_b32_e32 v96, v102
	v_mov_b32_e32 v97, v98
	v_pk_mul_f32 v[96:97], v[96:97], v[96:97]
	v_mul_f32_e32 v105, 0xbfb8aa3b, v104
	v_exp_f32_e32 v105, v105
	s_nop 0
	v_add_f32_e32 v105, 1.0, v105
	v_div_scale_f32 v108, s[8:9], v105, v105, v104
	v_rcp_f32_e32 v109, v108
	s_nop 0
	v_fma_f32 v162, -v108, v109, 1.0
	v_fmac_f32_e32 v109, v162, v109
	v_div_scale_f32 v162, vcc, v104, v105, v104
	v_mul_f32_e32 v163, v162, v109
	v_fma_f32 v165, -v108, v163, v162
	v_fmac_f32_e32 v163, v165, v109
	v_fma_f32 v108, -v108, v163, v162
	v_div_fmas_f32 v108, v108, v109, v163
	v_div_fixup_f32 v165, v108, v105, v104
	v_cvt_f32_f16_e32 v104, v228
	v_mul_f32_e32 v105, 0xbfb8aa3b, v104
	v_exp_f32_e32 v105, v105
	s_nop 0
	v_add_f32_e32 v105, 1.0, v105
	v_div_scale_f32 v108, s[8:9], v105, v105, v104
	v_rcp_f32_e32 v109, v108
	s_nop 0
	v_fma_f32 v162, -v108, v109, 1.0
	v_fmac_f32_e32 v109, v162, v109
	v_div_scale_f32 v162, vcc, v104, v105, v104
	v_mul_f32_e32 v163, v162, v109
	v_fma_f32 v166, -v108, v163, v162
	v_fmac_f32_e32 v163, v166, v109
	v_fma_f32 v108, -v108, v163, v162
	v_div_fmas_f32 v108, v108, v109, v163
	v_div_fixup_f32 v166, v108, v105, v104
	v_cvt_f32_f16_e32 v104, v227
	v_mul_f32_e32 v105, 0xbfb8aa3b, v104
	v_exp_f32_e32 v105, v105
	s_nop 0
	v_add_f32_e32 v105, 1.0, v105
	v_div_scale_f32 v108, s[8:9], v105, v105, v104
	v_rcp_f32_e32 v109, v108
	s_nop 0
	v_fma_f32 v162, -v108, v109, 1.0
	v_fmac_f32_e32 v109, v162, v109
	v_div_scale_f32 v162, vcc, v104, v105, v104
	v_mul_f32_e32 v163, v162, v109
	v_fma_f32 v167, -v108, v163, v162
	v_fmac_f32_e32 v163, v167, v109
	v_fma_f32 v108, -v108, v163, v162
	v_div_fmas_f32 v108, v108, v109, v163
	v_div_fixup_f32 v167, v108, v105, v104
	v_mov_b32_e32 v104, v111
	v_mov_b32_e32 v105, v107
	v_pk_mul_f32 v[104:105], v[104:105], v[104:105]
	v_mov_b32_e32 v108, v103
	v_mov_b32_e32 v109, v99
	v_pk_mul_f32 v[108:109], v[108:109], v[108:109]
	v_mov_b32_e32 v162, v104
	v_mov_b32_e32 v163, v100
	v_mov_b32_e32 v100, v105
	v_pk_add_f32 v[100:101], v[162:163], v[100:101]
	v_mov_b32_e32 v104, v108
	v_mov_b32_e32 v105, v96
	v_pk_add_f32 v[100:101], v[100:101], v[104:105]
	v_mov_b32_e32 v96, v109
	v_pk_add_f32 v[96:97], v[100:101], v[96:97]
	s_nop 1
	v_mov_b32_dpp v101, v97 quad_perm:[1,0,3,2] row_mask:0xf bank_mask:0xf bound_ctrl:1
	v_mov_b32_dpp v100, v96 quad_perm:[1,0,3,2] row_mask:0xf bank_mask:0xf bound_ctrl:1
	v_pk_add_f32 v[96:97], v[96:97], v[100:101]
	s_nop 1
	v_mov_b32_dpp v101, v97 quad_perm:[2,3,0,1] row_mask:0xf bank_mask:0xf bound_ctrl:1
	v_mov_b32_dpp v100, v96 quad_perm:[2,3,0,1] row_mask:0xf bank_mask:0xf bound_ctrl:1
	v_pk_add_f32 v[96:97], v[96:97], v[100:101]
	s_nop 1
	v_mov_b32_dpp v101, v97 row_ror:4 row_mask:0xf bank_mask:0xf bound_ctrl:1
	v_mov_b32_dpp v100, v96 row_ror:4 row_mask:0xf bank_mask:0xf bound_ctrl:1
	v_pk_add_f32 v[96:97], v[96:97], v[100:101]
	s_nop 1
	v_mov_b32_dpp v101, v97 row_ror:8 row_mask:0xf bank_mask:0xf bound_ctrl:1
	v_mov_b32_dpp v100, v96 row_ror:8 row_mask:0xf bank_mask:0xf bound_ctrl:1
	v_pk_add_f32 v[96:97], v[96:97], v[100:101]
	s_nop 0
	v_pk_fma_f32 v[96:97], v[96:97], s[0:1], v[170:171] op_sel_hi:[1,0,0]
	s_nop 0
	v_mul_f32_e32 v100, 0x4b800000, v97
	v_cmp_gt_f32_e64 s[8:9], s49, v97
	v_cmp_gt_f32_e32 vcc, s49, v96
	s_nop 0
	v_cndmask_b32_e64 v97, v97, v100, s[8:9]
	v_rsq_f32_e32 v97, v97
	s_nop 0
	v_mul_f32_e32 v100, 0x45800000, v97
	v_cndmask_b32_e64 v97, v97, v100, s[8:9]
	v_mul_f32_e32 v100, v110, v97
	v_mul_f32_e32 v100, v238, v100
	v_mul_f32_e32 v100, v164, v100
	v_med3_f32 v100, v100, s57, v194
	v_cvt_f16_f32_e32 v100, v100
	global_store_short v[160:161], v100, off
	v_mul_f32_e32 v100, v106, v97
	v_mul_f32_e32 v100, v237, v100
	v_mul_f32_e32 v100, v165, v100
	v_med3_f32 v100, v100, s57, v194
	v_cvt_f16_f32_e32 v100, v100
	global_store_short v[158:159], v100, off
	v_mul_f32_e32 v100, v102, v97
	v_mul_f32_e32 v97, v98, v97
	v_mul_f32_e32 v97, v235, v97
	v_mul_f32_e32 v97, v167, v97
	v_med3_f32 v97, v97, s57, v194
	v_cvt_f16_f32_e32 v97, v97
	v_mul_f32_e32 v100, v236, v100
	v_mul_f32_e32 v100, v166, v100
	v_med3_f32 v100, v100, s57, v194
	global_store_short v[154:155], v97, off
	v_mul_f32_e32 v97, 0x4b800000, v96
	v_cndmask_b32_e32 v96, v96, v97, vcc
	v_rsq_f32_e32 v96, v96
	v_cvt_f16_f32_e32 v100, v100
	v_mul_f32_e32 v97, 0x45800000, v96
	v_cndmask_b32_e32 v96, v96, v97, vcc
	v_cvt_f32_f16_e32 v97, v226
	global_store_short v[156:157], v100, off
	v_mul_f32_e32 v98, v111, v96
	v_mul_f32_e32 v98, v238, v98
	v_mul_f32_e32 v100, 0xbfb8aa3b, v97
	v_exp_f32_e32 v100, v100
	s_nop 0
	v_add_f32_e32 v100, 1.0, v100
	v_div_scale_f32 v101, s[8:9], v100, v100, v97
	v_rcp_f32_e32 v102, v101
	s_nop 0
	v_fma_f32 v104, -v101, v102, 1.0
	v_fmac_f32_e32 v102, v104, v102
	v_div_scale_f32 v104, vcc, v97, v100, v97
	v_mul_f32_e32 v105, v104, v102
	v_fma_f32 v106, -v101, v105, v104
	v_fmac_f32_e32 v105, v106, v102
	v_fma_f32 v101, -v101, v105, v104
	v_div_fmas_f32 v101, v101, v102, v105
	v_div_fixup_f32 v97, v101, v100, v97
	v_mul_f32_e32 v97, v97, v98
	v_med3_f32 v97, v97, s57, v194
	v_cvt_f16_f32_e32 v97, v97
	v_mul_f32_e32 v98, v107, v96
	v_mul_f32_e32 v98, v237, v98
	global_store_short v[152:153], v97, off
	v_cvt_f32_f16_e32 v97, v225
	v_mul_f32_e32 v100, 0xbfb8aa3b, v97
	v_exp_f32_e32 v100, v100
	s_nop 0
	v_add_f32_e32 v100, 1.0, v100
	v_div_scale_f32 v101, s[8:9], v100, v100, v97
	v_rcp_f32_e32 v102, v101
	s_nop 0
	v_fma_f32 v104, -v101, v102, 1.0
	v_fmac_f32_e32 v102, v104, v102
	v_div_scale_f32 v104, vcc, v97, v100, v97
	v_mul_f32_e32 v105, v104, v102
	v_fma_f32 v106, -v101, v105, v104
	v_fmac_f32_e32 v105, v106, v102
	v_fma_f32 v101, -v101, v105, v104
	v_div_fmas_f32 v101, v101, v102, v105
	v_div_fixup_f32 v97, v101, v100, v97
	v_mul_f32_e32 v97, v97, v98
	v_med3_f32 v97, v97, s57, v194
	v_cvt_f16_f32_e32 v97, v97
	v_mul_f32_e32 v98, v103, v96
	v_mul_f32_e32 v98, v236, v98
	v_mul_f32_e32 v96, v99, v96
	global_store_short v[150:151], v97, off
	v_cvt_f32_f16_e32 v97, v224
	v_mul_f32_e32 v96, v235, v96
	v_mul_f32_e32 v100, 0xbfb8aa3b, v97
	v_exp_f32_e32 v100, v100
	s_nop 0
	v_add_f32_e32 v100, 1.0, v100
	v_div_scale_f32 v101, s[8:9], v100, v100, v97
	v_rcp_f32_e32 v102, v101
	s_nop 0
	v_fma_f32 v103, -v101, v102, 1.0
	v_fmac_f32_e32 v102, v103, v102
	v_div_scale_f32 v103, vcc, v97, v100, v97
	v_mul_f32_e32 v104, v103, v102
	v_fma_f32 v105, -v101, v104, v103
	v_fmac_f32_e32 v104, v105, v102
	v_fma_f32 v101, -v101, v104, v103
	v_div_fmas_f32 v101, v101, v102, v104
	v_div_fixup_f32 v97, v101, v100, v97
	v_mul_f32_e32 v97, v97, v98
	v_med3_f32 v97, v97, s57, v194
	v_cvt_f16_f32_e32 v97, v97
	global_store_short v[148:149], v97, off
	v_cvt_f32_f16_e32 v97, v223
	v_mul_f32_e32 v98, 0xbfb8aa3b, v97
	v_exp_f32_e32 v98, v98
	s_nop 0
	v_add_f32_e32 v98, 1.0, v98
	v_div_scale_f32 v99, s[8:9], v98, v98, v97
	v_rcp_f32_e32 v100, v99
	s_nop 0
	v_fma_f32 v101, -v99, v100, 1.0
	v_fmac_f32_e32 v100, v101, v100
	v_div_scale_f32 v101, vcc, v97, v98, v97
	v_mul_f32_e32 v102, v101, v100
	v_fma_f32 v103, -v99, v102, v101
	v_fmac_f32_e32 v102, v103, v100
	v_fma_f32 v99, -v99, v102, v101
	v_div_fmas_f32 v99, v99, v100, v102
	v_div_fixup_f32 v97, v99, v98, v97
	v_mul_f32_e32 v96, v97, v96
	v_med3_f32 v96, v96, s57, v194
	v_cvt_f16_f32_e32 v96, v96
	s_andn2_b64 vcc, exec, s[10:11]
	global_store_short v[146:147], v96, off
	ds_read_b128 v[96:99], v116 offset:55296
	ds_read_b128 v[240:243], v117 offset:36864
	ds_read_b128 v[244:247], v117 offset:39168
	ds_read_b128 v[252:255], v117 offset:41472
	s_waitcnt lgkmcnt(2)
	v_mfma_f32_16x16x32_f16 v[80:83], v[96:99], v[240:243], v[80:83]
	ds_read_b128 v[240:243], v117 offset:43776
	ds_read_b128 v[100:103], v116 offset:55360
	s_waitcnt lgkmcnt(3)
	v_mfma_f32_16x16x32_f16 v[84:87], v[96:99], v[244:247], v[84:87]
	ds_read_b128 v[244:247], v117 offset:36928
	s_waitcnt lgkmcnt(3)
	v_mfma_f32_16x16x32_f16 v[88:91], v[96:99], v[252:255], v[88:91]
	ds_read_b128 v[252:255], v117 offset:39232
	s_waitcnt lgkmcnt(3)
	v_mfma_f32_16x16x32_f16 v[92:95], v[96:99], v[240:243], v[92:95]
	ds_read_b128 v[240:243], v117 offset:41536
	s_waitcnt lgkmcnt(2)
	v_mfma_f32_16x16x32_f16 v[80:83], v[100:103], v[244:247], v[80:83]
	ds_read_b128 v[244:247], v117 offset:43840
	s_waitcnt lgkmcnt(2)
	v_mfma_f32_16x16x32_f16 v[84:87], v[100:103], v[252:255], v[84:87]
	s_waitcnt lgkmcnt(1)
	v_mfma_f32_16x16x32_f16 v[88:91], v[100:103], v[240:243], v[88:91]
	s_waitcnt lgkmcnt(0)
	s_barrier
	v_mfma_f32_16x16x32_f16 v[92:95], v[100:103], v[244:247], v[92:95]
	v_max_f32_e32 v96, v80, v80
	v_med3_f32 v96, v96, s57, v194
	v_cvt_f16_f32_e32 v96, v96
	ds_write_b16 v215, v96 offset:46080
	v_max_f32_e32 v96, v81, v81
	v_med3_f32 v96, v96, s57, v194
	v_cvt_f16_f32_e32 v96, v96
	ds_write_b16 v215, v96 offset:46224
	v_max_f32_e32 v96, v82, v82
	v_med3_f32 v96, v96, s57, v194
	v_cvt_f16_f32_e32 v96, v96
	ds_write_b16 v215, v96 offset:46368
	v_max_f32_e32 v96, v83, v83
	v_med3_f32 v96, v96, s57, v194
	v_cvt_f16_f32_e32 v96, v96
	ds_write_b16 v215, v96 offset:46512
	v_max_f32_e32 v96, v84, v84
	v_med3_f32 v96, v96, s57, v194
	v_cvt_f16_f32_e32 v96, v96
	ds_write_b16 v215, v96 offset:46112
	v_max_f32_e32 v96, v85, v85
	v_med3_f32 v96, v96, s57, v194
	v_cvt_f16_f32_e32 v96, v96
	ds_write_b16 v216, v96 offset:46224
	v_max_f32_e32 v96, v86, v86
	v_med3_f32 v96, v96, s57, v194
	v_cvt_f16_f32_e32 v96, v96
	ds_write_b16 v216, v96 offset:46368
	v_max_f32_e32 v96, v87, v87
	v_med3_f32 v96, v96, s57, v194
	v_cvt_f16_f32_e32 v96, v96
	ds_write_b16 v216, v96 offset:46512
	v_max_f32_e32 v96, v88, v88
	v_med3_f32 v96, v96, s57, v194
	v_cvt_f16_f32_e32 v96, v96
	ds_write_b16 v215, v96 offset:46144
	v_max_f32_e32 v96, v89, v89
	v_med3_f32 v96, v96, s57, v194
	v_cvt_f16_f32_e32 v96, v96
	ds_write_b16 v217, v96 offset:46224
	v_max_f32_e32 v96, v90, v90
	v_med3_f32 v96, v96, s57, v194
	v_cvt_f16_f32_e32 v96, v96
	ds_write_b16 v217, v96 offset:46368
	v_max_f32_e32 v96, v91, v91
	v_med3_f32 v96, v96, s57, v194
	v_cvt_f16_f32_e32 v96, v96
	ds_write_b16 v217, v96 offset:46512
	v_max_f32_e32 v96, v92, v92
	v_med3_f32 v96, v96, s57, v194
	v_cvt_f16_f32_e32 v96, v96
	ds_write_b16 v215, v96 offset:46176
	v_max_f32_e32 v96, v93, v93
	v_med3_f32 v96, v96, s57, v194
	v_cvt_f16_f32_e32 v96, v96
	ds_write_b16 v218, v96 offset:46224
	v_max_f32_e32 v96, v94, v94
	v_med3_f32 v96, v96, s57, v194
	v_cvt_f16_f32_e32 v96, v96
	ds_write_b16 v218, v96 offset:46368
	v_max_f32_e32 v96, v95, v95
	v_med3_f32 v96, v96, s57, v194
	v_cvt_f16_f32_e32 v96, v96
	ds_write_b16 v218, v96 offset:46512
	s_cbranch_vccnz .LBB0_520
	ds_write_b128 v220, v[56:59]
	ds_write_b128 v211, v[60:63]
	ds_write_b128 v221, v[64:67]
	ds_write_b128 v212, v[68:71]
	ds_write_b128 v222, v[72:75]
	ds_write_b128 v213, v[76:79]
	s_branch .LBB0_520
